# attend fast path + dscan step loop: prefetch loads no longer waited right after issue (global loads, masks applied at next step, u/gtot landed in final regs)
# speedup vs baseline: 1.0380x; 1.0071x over previous
.LBB0_242:
	s_and_b32 s64, s81, 1
	s_add_i32 s80, s81, 1
	s_cmp_lt_u32 s80, s78
	s_cselect_b64 s[62:63], -1, 0
	s_cmp_ge_u32 s80, s78
	s_cbranch_scc1 .LBB0_245
	s_xor_b32 s60, s64, 1
	s_mul_i32 s60, s60, 0xf400
	s_add_i32 s60, s60, 0
	v_add_u32_e32 v95, 0x2200, v163
	v_add3_u32 v94, s60, v163, v172
	v_add3_u32 v95, s60, v95, v172
	s_waitcnt vmcnt(0)
	v_cndmask_b32_e64 v53, 0, v53, s[8:9]
	v_cndmask_b32_e64 v52, 0, v52, s[8:9]
	v_cndmask_b32_e64 v51, 0, v51, s[8:9]
	v_cndmask_b32_e64 v50, 0, v50, s[8:9]
	v_cndmask_b32_e64 v57, 0, v57, s[10:11]
	v_cndmask_b32_e64 v56, 0, v56, s[10:11]
	v_cndmask_b32_e64 v55, 0, v55, s[10:11]
	v_cndmask_b32_e64 v54, 0, v54, s[10:11]
	v_cndmask_b32_e64 v61, 0, v61, s[8:9]
	v_cndmask_b32_e64 v60, 0, v60, s[8:9]
	v_cndmask_b32_e64 v59, 0, v59, s[8:9]
	v_cndmask_b32_e64 v58, 0, v58, s[8:9]
	v_cndmask_b32_e64 v65, 0, v65, s[10:11]
	v_cndmask_b32_e64 v64, 0, v64, s[10:11]
	v_cndmask_b32_e64 v63, 0, v63, s[10:11]
	v_cndmask_b32_e64 v62, 0, v62, s[10:11]
	ds_write_b128 v94, v[50:53]
	ds_write_b128 v95, v[54:57]
	ds_write_b128 v94, v[58:61] offset:17408
	ds_write_b128 v95, v[62:65] offset:17408
	v_add_u32_e32 v95, 0x2400, v173
	v_add3_u32 v94, s60, v173, v136
	v_add3_u32 v95, s60, v95, v136
	s_waitcnt vmcnt(0)
	ds_write_b128 v94, v[66:69] offset:34816
	ds_write_b128 v95, v[70:73] offset:34816
	ds_write_b128 v94, v[74:77] offset:53248
	s_add_i32 s60, s81, 2
	s_cmp_ge_u32 s60, s78
	s_cbranch_scc0 .LBB0_246

.LBB0_246:
	s_add_i32 s60, s86, s81
	s_add_i32 s60, s60, 2
	v_add_u32_e32 v50, s59, v217
	v_add_u32_e32 v54, s59, v216
	s_ashr_i32 s61, s60, 31
	v_ashrrev_i32_e32 v51, 31, v50
	v_ashrrev_i32_e32 v55, 31, v54
	s_lshl_b64 s[66:67], s[60:61], 14
	v_lshlrev_b64 v[58:59], 10, v[50:51]
	v_lshlrev_b64 v[62:63], 10, v[54:55]
	s_add_u32 s66, s69, s66
	v_or_b32_e32 v58, v58, v238
	v_or_b32_e32 v62, v62, v238
	s_addc_u32 s67, s70, s67
	v_lshl_add_u64 v[50:51], s[88:89], 0, v[58:59]
	v_lshl_add_u64 v[54:55], s[88:89], 0, v[62:63]
	v_lshl_add_u64 v[58:59], s[90:91], 0, v[58:59]
	v_lshl_add_u64 v[62:63], s[90:91], 0, v[62:63]
	s_waitcnt vmcnt(0)
	v_lshl_add_u64 v[66:67], v[132:133], 1, s[66:67]
	v_lshl_add_u64 v[70:71], v[134:135], 1, s[66:67]
	s_lshl_b64 s[60:61], s[60:61], 13
	global_load_dwordx4 v[50:53], v[50:51], off
	v_lshl_add_u64 v[66:67], v[66:67], 0, v[0:1]
	global_load_dwordx4 v[54:57], v[54:55], off
	v_lshl_add_u64 v[70:71], v[70:71], 0, v[0:1]
	global_load_dwordx4 v[58:61], v[58:59], off
	v_lshl_add_u64 v[74:75], v[138:139], 0, s[60:61]
	global_load_dwordx4 v[62:65], v[62:63], off
	global_load_dwordx4 v[66:69], v[66:67], off
	global_load_dwordx4 v[70:73], v[70:71], off
	global_load_dwordx4 v[74:77], v[74:75], off
	s_and_saveexec_b64 s[60:61], s[4:5]
	s_cbranch_execz .LBB0_308
.LBB0_247:
	s_andn2_b64 vcc, exec, s[62:63]
	s_cbranch_vccnz .LBB0_252
	s_add_i32 s62, s86, s81
	s_add_i32 s62, s62, 1
	s_ashr_i32 s63, s62, 31
	s_lshl_b64 s[62:63], s[62:63], 2
	s_add_u32 s62, s71, s62
	s_addc_u32 s63, s72, s63
	v_mov_b64_e32 v[26:27], s[62:63]
	global_load_dword v239, v[26:27], off
	s_and_b64 vcc, exec, s[12:13]
	s_mov_b64 s[62:63], -1
	s_cbranch_vccnz .LBB0_250
	v_add_u32_e32 v26, s59, v237
	v_add_u32_e32 v34, s59, v230
	v_add_u32_e32 v36, s59, v229
	v_ashrrev_i32_e32 v27, 31, v26
	v_add_u32_e32 v28, s59, v233
	v_add_u32_e32 v30, s59, v232
	v_add_u32_e32 v32, s59, v231
	v_ashrrev_i32_e32 v35, 31, v34
	v_ashrrev_i32_e32 v37, 31, v36
	v_add_u32_e32 v38, s59, v228
	v_add_u32_e32 v40, s59, v227
	v_lshlrev_b64 v[26:27], 10, v[26:27]
	v_ashrrev_i32_e32 v29, 31, v28
	v_ashrrev_i32_e32 v31, 31, v30
	v_ashrrev_i32_e32 v33, 31, v32
	v_lshlrev_b64 v[34:35], 10, v[34:35]
	v_lshlrev_b64 v[36:37], 10, v[36:37]
	v_ashrrev_i32_e32 v39, 31, v38
	v_ashrrev_i32_e32 v41, 31, v40
	v_lshl_add_u64 v[26:27], v[164:165], 0, v[26:27]
	v_lshlrev_b64 v[28:29], 10, v[28:29]
	v_lshlrev_b64 v[30:31], 10, v[30:31]
	v_lshlrev_b64 v[32:33], 10, v[32:33]
	v_lshl_add_u64 v[34:35], v[164:165], 0, v[34:35]
	v_lshl_add_u64 v[36:37], v[164:165], 0, v[36:37]
	v_lshlrev_b64 v[38:39], 10, v[38:39]
	v_lshlrev_b64 v[40:41], 10, v[40:41]
	v_lshl_add_u64 v[28:29], v[164:165], 0, v[28:29]
	v_lshl_add_u64 v[30:31], v[164:165], 0, v[30:31]
	v_lshl_add_u64 v[32:33], v[164:165], 0, v[32:33]
	v_lshl_add_u64 v[38:39], v[164:165], 0, v[38:39]
	v_lshl_add_u64 v[40:41], v[164:165], 0, v[40:41]
	flat_load_ushort v94, v[26:27]
	flat_load_ushort v95, v[28:29]
	flat_load_ushort v96, v[30:31]
	flat_load_ushort v97, v[32:33]
	s_nop 0
	flat_load_ushort v34, v[34:35]
	s_nop 0
	flat_load_ushort v35, v[36:37]
	s_nop 0
	flat_load_ushort v36, v[38:39]
	flat_load_ushort v37, v[40:41]
	v_add_u32_e32 v26, s59, v226
	v_ashrrev_i32_e32 v27, 31, v26
	v_add_u32_e32 v28, s59, v225
	v_add_u32_e32 v30, s59, v224
	v_lshlrev_b64 v[26:27], 10, v[26:27]
	v_ashrrev_i32_e32 v29, 31, v28
	v_ashrrev_i32_e32 v31, 31, v30
	v_lshl_add_u64 v[26:27], v[164:165], 0, v[26:27]
	v_lshlrev_b64 v[28:29], 10, v[28:29]
	v_lshlrev_b64 v[30:31], 10, v[30:31]
	v_lshl_add_u64 v[28:29], v[164:165], 0, v[28:29]
	v_lshl_add_u64 v[30:31], v[164:165], 0, v[30:31]
	flat_load_ushort v38, v[26:27]
	flat_load_ushort v39, v[28:29]
	flat_load_ushort v40, v[30:31]
	v_add_u32_e32 v26, s59, v223
	v_ashrrev_i32_e32 v27, 31, v26
	v_add_u32_e32 v28, s59, v222
	v_add_u32_e32 v30, s59, v221
	v_add_u32_e32 v32, s59, v220
	v_lshlrev_b64 v[26:27], 10, v[26:27]
	v_ashrrev_i32_e32 v29, 31, v28
	v_ashrrev_i32_e32 v31, 31, v30
	v_ashrrev_i32_e32 v33, 31, v32
	v_lshl_add_u64 v[26:27], v[164:165], 0, v[26:27]
	v_lshlrev_b64 v[28:29], 10, v[28:29]
	v_lshlrev_b64 v[30:31], 10, v[30:31]
	v_lshlrev_b64 v[32:33], 10, v[32:33]
	v_lshl_add_u64 v[28:29], v[164:165], 0, v[28:29]
	v_lshl_add_u64 v[30:31], v[164:165], 0, v[30:31]
	v_lshl_add_u64 v[32:33], v[164:165], 0, v[32:33]
	flat_load_ushort v41, v[26:27]
	flat_load_ushort v98, v[28:29]
	flat_load_ushort v99, v[30:31]
	flat_load_ushort v100, v[32:33]
	v_add_u32_e32 v26, s59, v218
	v_ashrrev_i32_e32 v27, 31, v26
	v_lshlrev_b64 v[26:27], 10, v[26:27]
	v_lshl_add_u64 v[26:27], v[164:165], 0, v[26:27]
	flat_load_ushort v101, v[26:27]
	s_mov_b64 s[62:63], 0
	s_waitcnt vmcnt(0) lgkmcnt(0)
	v_lshlrev_b32_e32 v26, 16, v94
	v_lshlrev_b32_e32 v27, 16, v95
	v_lshlrev_b32_e32 v28, 16, v96
	v_lshlrev_b32_e32 v29, 16, v97
	v_lshlrev_b32_e32 v30, 16, v34
	v_lshlrev_b32_e32 v31, 16, v35
	v_lshlrev_b32_e32 v32, 16, v36
	v_lshlrev_b32_e32 v33, 16, v37
	v_cndmask_b32_e64 v26, 0, v26, s[2:3]
	v_cndmask_b32_e64 v27, 0, v27, s[16:17]
	v_cndmask_b32_e64 v28, 0, v28, s[18:19]
	v_cndmask_b32_e64 v29, 0, v29, s[20:21]
	v_cndmask_b32_e64 v30, 0, v30, s[22:23]
	v_cndmask_b32_e64 v31, 0, v31, s[24:25]
	v_cndmask_b32_e64 v32, 0, v32, s[26:27]
	v_cndmask_b32_e64 v33, 0, v33, s[28:29]
	v_lshlrev_b32_e32 v34, 16, v38
	v_lshlrev_b32_e32 v35, 16, v39
	v_lshlrev_b32_e32 v36, 16, v40
	v_cndmask_b32_e64 v34, 0, v34, s[30:31]
	v_cndmask_b32_e64 v35, 0, v35, s[34:35]
	v_cndmask_b32_e64 v36, 0, v36, s[36:37]
	v_lshlrev_b32_e32 v37, 16, v41
	v_lshlrev_b32_e32 v38, 16, v98
	v_lshlrev_b32_e32 v39, 16, v99
	v_lshlrev_b32_e32 v40, 16, v100
	v_cndmask_b32_e64 v37, 0, v37, s[38:39]
	v_cndmask_b32_e64 v38, 0, v38, s[40:41]
	v_cndmask_b32_e64 v39, 0, v39, s[42:43]
	v_cndmask_b32_e64 v40, 0, v40, s[44:45]
	v_lshlrev_b32_e32 v41, 16, v101
	v_cndmask_b32_e64 v41, 0, v41, s[46:47]
.LBB0_250:
	s_andn2_b64 vcc, exec, s[62:63]
	s_cbranch_vccnz .LBB0_252
	v_add_u32_e32 v94, s59, v214
	v_add_u32_e32 v102, 64, v94
	v_add_u32_e32 v116, 0x53, v94
	v_ashrrev_i32_e32 v103, 31, v102
	v_add_u32_e32 v104, 0x41, v94
	v_add_u32_e32 v106, 0x42, v94
	v_add_u32_e32 v108, 0x43, v94
	v_add_u32_e32 v110, 0x50, v94
	v_add_u32_e32 v112, 0x51, v94
	v_add_u32_e32 v114, 0x52, v94
	v_ashrrev_i32_e32 v117, 31, v116
	v_lshlrev_b64 v[102:103], 10, v[102:103]
	v_ashrrev_i32_e32 v105, 31, v104
	v_ashrrev_i32_e32 v107, 31, v106
	v_ashrrev_i32_e32 v109, 31, v108
	v_ashrrev_i32_e32 v111, 31, v110
	v_ashrrev_i32_e32 v113, 31, v112
	v_ashrrev_i32_e32 v115, 31, v114
	v_lshlrev_b64 v[116:117], 10, v[116:117]
	v_lshl_add_u64 v[102:103], v[164:165], 0, v[102:103]
	v_lshlrev_b64 v[104:105], 10, v[104:105]
	v_lshlrev_b64 v[106:107], 10, v[106:107]
	v_lshlrev_b64 v[108:109], 10, v[108:109]
	v_lshlrev_b64 v[110:111], 10, v[110:111]
	v_lshlrev_b64 v[112:113], 10, v[112:113]
	v_lshlrev_b64 v[114:115], 10, v[114:115]
	v_lshl_add_u64 v[116:117], v[164:165], 0, v[116:117]
	v_lshl_add_u64 v[104:105], v[164:165], 0, v[104:105]
	v_lshl_add_u64 v[106:107], v[164:165], 0, v[106:107]
	v_lshl_add_u64 v[108:109], v[164:165], 0, v[108:109]
	v_lshl_add_u64 v[110:111], v[164:165], 0, v[110:111]
	v_lshl_add_u64 v[112:113], v[164:165], 0, v[112:113]
	v_lshl_add_u64 v[114:115], v[164:165], 0, v[114:115]
	global_load_ushort v26, v[102:103], off
	global_load_ushort v27, v[104:105], off
	global_load_ushort v28, v[106:107], off
	global_load_ushort v29, v[108:109], off
	global_load_ushort v30, v[110:111], off
	global_load_ushort v31, v[112:113], off
	global_load_ushort v32, v[114:115], off
	global_load_ushort v33, v[116:117], off
	v_add_u32_e32 v102, 0x60, v94
	v_add_u32_e32 v116, 0x73, v94
	v_ashrrev_i32_e32 v103, 31, v102
	v_add_u32_e32 v104, 0x61, v94
	v_add_u32_e32 v106, 0x62, v94
	v_add_u32_e32 v108, 0x63, v94
	v_add_u32_e32 v110, 0x70, v94
	v_add_u32_e32 v112, 0x71, v94
	v_add_u32_e32 v114, 0x72, v94
	v_ashrrev_i32_e32 v117, 31, v116
	v_lshlrev_b64 v[102:103], 10, v[102:103]
	v_ashrrev_i32_e32 v105, 31, v104
	v_ashrrev_i32_e32 v107, 31, v106
	v_ashrrev_i32_e32 v109, 31, v108
	v_ashrrev_i32_e32 v111, 31, v110
	v_ashrrev_i32_e32 v113, 31, v112
	v_ashrrev_i32_e32 v115, 31, v114
	v_lshlrev_b64 v[116:117], 10, v[116:117]
	v_lshl_add_u64 v[102:103], v[164:165], 0, v[102:103]
	v_lshlrev_b64 v[104:105], 10, v[104:105]
	v_lshlrev_b64 v[106:107], 10, v[106:107]
	v_lshlrev_b64 v[108:109], 10, v[108:109]
	v_lshlrev_b64 v[110:111], 10, v[110:111]
	v_lshlrev_b64 v[112:113], 10, v[112:113]
	v_lshlrev_b64 v[114:115], 10, v[114:115]
	v_lshl_add_u64 v[116:117], v[164:165], 0, v[116:117]
	v_lshl_add_u64 v[104:105], v[164:165], 0, v[104:105]
	v_lshl_add_u64 v[106:107], v[164:165], 0, v[106:107]
	v_lshl_add_u64 v[108:109], v[164:165], 0, v[108:109]
	v_lshl_add_u64 v[110:111], v[164:165], 0, v[110:111]
	v_lshl_add_u64 v[112:113], v[164:165], 0, v[112:113]
	v_lshl_add_u64 v[114:115], v[164:165], 0, v[114:115]
	global_load_ushort v34, v[102:103], off
	global_load_ushort v35, v[104:105], off
	global_load_ushort v36, v[106:107], off
	global_load_ushort v37, v[108:109], off
	global_load_ushort v38, v[110:111], off
	global_load_ushort v39, v[112:113], off
	global_load_ushort v40, v[114:115], off
	s_nop 0
	global_load_ushort v41, v[116:117], off
.LBB0_252:
	s_mul_i32 s64, s64, 0xf400
	v_add_u32_e32 v240, s64, v208
	v_add_u32_e32 v242, v240, v203
	ds_read2_b64 v[94:97], v242 offset1:4
	ds_read2_b64 v[110:113], v242 offset0:8 offset1:12
	v_cvt_pk_bf16_f32 v98, v2, v3
	v_cvt_pk_bf16_f32 v99, v4, v5
	v_cvt_pk_bf16_f32 v100, v6, v7
	v_cvt_pk_bf16_f32 v101, v8, v9
	ds_read2_b64 v[114:117], v242 offset0:16 offset1:20
	v_cvt_pk_bf16_f32 v102, v10, v11
	v_cvt_pk_bf16_f32 v103, v12, v13
	s_waitcnt lgkmcnt(0)
	v_mfma_f32_16x16x32_bf16 v[94:97], v[94:97], v[98:101], 0
	v_cvt_pk_bf16_f32 v104, v14, v15
	v_cvt_pk_bf16_f32 v105, v16, v17
	ds_read2_b64 v[118:121], v242 offset0:24 offset1:28
	v_cvt_pk_bf16_f32 v106, v18, v19
	v_mfma_f32_16x16x32_bf16 v[94:97], v[110:113], v[102:105], v[94:97]
	v_cvt_pk_bf16_f32 v107, v20, v21
	v_cvt_pk_bf16_f32 v108, v22, v23
	v_cvt_pk_bf16_f32 v109, v24, v25
	v_add_u32_e32 v126, 0x1000, v242
	v_cvt_pk_bf16_f32 v110, v42, v43
	v_mfma_f32_16x16x32_bf16 v[94:97], v[114:117], v[106:109], v[94:97]
	ds_read2_b64 v[114:117], v126 offset0:32 offset1:36
	v_cvt_pk_bf16_f32 v111, v44, v45
	v_cvt_pk_bf16_f32 v112, v46, v47
	v_cvt_pk_bf16_f32 v113, v48, v49
	ds_read2_b64 v[122:125], v126 offset0:48 offset1:52
	s_waitcnt lgkmcnt(1)
	v_mfma_f32_16x16x32_bf16 v[114:117], v[114:117], v[98:101], 0
	v_add_u32_e32 v146, 0x2000, v242
	v_add_u32_e32 v244, v240, v204
	ds_read2_b64 v[168:171], v244 offset1:4
	v_mfma_f32_16x16x32_bf16 v[94:97], v[118:121], v[110:113], v[94:97]
	ds_read2_b64 v[118:121], v126 offset0:40 offset1:44
	v_add_u32_e32 v241, v240, v205
	s_and_b64 vcc, exec, s[12:13]
	s_waitcnt lgkmcnt(0)
	v_mfma_f32_16x16x32_bf16 v[114:117], v[118:121], v[102:105], v[114:117]
	ds_read2_b64 v[118:121], v126 offset0:56 offset1:60
	ds_read2_b64 v[126:129], v146 offset0:80 offset1:84
	s_nop 0
	v_sub_f32_e32 v97, v81, v97
	v_mfma_f32_16x16x32_bf16 v[114:117], v[122:125], v[106:109], v[114:117]
	ds_read2_b64 v[122:125], v146 offset0:64 offset1:68
	v_sub_f32_e32 v96, v80, v96
	v_sub_f32_e32 v95, v79, v95
	s_waitcnt lgkmcnt(2)
	v_mfma_f32_16x16x32_bf16 v[114:117], v[118:121], v[110:113], v[114:117]
	ds_read2_b64 v[118:121], v146 offset0:72 offset1:76
	v_sub_f32_e32 v94, v78, v94
	s_waitcnt lgkmcnt(1)
	v_mfma_f32_16x16x32_bf16 v[122:125], v[122:125], v[98:101], 0
	s_nop 3
	v_sub_f32_e32 v117, v85, v117
	v_sub_f32_e32 v116, v84, v116
	v_sub_f32_e32 v115, v83, v115
	s_waitcnt lgkmcnt(0)
	v_mfma_f32_16x16x32_bf16 v[118:121], v[118:121], v[102:105], v[122:125]
	v_sub_f32_e32 v114, v82, v114
	s_nop 1
	ds_read2_b64 v[122:125], v146 offset0:88 offset1:92
	v_add_u32_e32 v146, 0x5000, v242
	v_mfma_f32_16x16x32_bf16 v[118:121], v[126:129], v[106:109], v[118:121]
	ds_read2_b64 v[126:129], v244 offset0:8 offset1:12
	ds_read2_b64 v[246:249], v244 offset0:16 offset1:20
	ds_read2_b64 v[176:179], v244 offset0:24 offset1:28
	s_waitcnt lgkmcnt(3)
	v_mfma_f32_16x16x32_bf16 v[118:121], v[122:125], v[110:113], v[118:121]
	v_mfma_f32_16x16x32_bf16 v[122:125], v[168:171], v[98:101], 0
	s_nop 6
	v_sub_f32_e32 v86, v86, v118
	v_add_u32_e32 v118, 0x4000, v242
	ds_read2_b64 v[82:85], v118 offset0:128 offset1:132
	s_waitcnt lgkmcnt(3)
	v_mfma_f32_16x16x32_bf16 v[78:81], v[126:129], v[102:105], v[122:125]
	v_sub_f32_e32 v87, v87, v119
	v_sub_f32_e32 v121, v89, v121
	v_sub_f32_e32 v120, v88, v120
	s_waitcnt lgkmcnt(2)
	v_mfma_f32_16x16x32_bf16 v[78:81], v[246:249], v[106:109], v[78:81]
	v_add_u32_e32 v168, s59, v214
	s_waitcnt lgkmcnt(1)
	v_mfma_f32_16x16x32_bf16 v[78:81], v[176:179], v[110:113], v[78:81]
	s_waitcnt lgkmcnt(0)
	v_mfma_f32_16x16x32_bf16 v[82:85], v[82:85], v[98:101], 0
	s_nop 5
	v_sub_f32_e32 v90, v90, v78
	v_cvt_pk_bf16_f32 v78, v94, v95
	v_cvt_pk_bf16_f32 v94, v86, v87
	ds_read2_b64 v[86:89], v118 offset0:136 offset1:140
	v_sub_f32_e32 v93, v93, v81
	v_sub_f32_e32 v92, v92, v80
	v_sub_f32_e32 v91, v91, v79
	v_cvt_pk_bf16_f32 v79, v96, v97
	v_cvt_pk_bf16_f32 v96, v90, v91
	v_cvt_pk_bf16_f32 v97, v92, v93
	ds_read2_b64 v[90:93], v118 offset0:144 offset1:148
	v_cvt_pk_bf16_f32 v80, v114, v115
	v_cvt_pk_bf16_f32 v81, v116, v117
	ds_read2_b64 v[114:117], v118 offset0:152 offset1:156
	s_waitcnt lgkmcnt(2)
	v_mfma_f32_16x16x32_bf16 v[82:85], v[86:89], v[102:105], v[82:85]
	v_add_u32_e32 v86, 0xd000, v241
	ds_read2_b64 v[122:125], v86 offset1:4
	ds_read2_b64 v[126:129], v86 offset0:8 offset1:12
	v_cvt_pk_bf16_f32 v95, v120, v121
	s_waitcnt lgkmcnt(3)
	v_mfma_f32_16x16x32_bf16 v[90:93], v[90:93], v[106:109], v[82:85]
	ds_read2_b64 v[86:89], v146 offset0:160 offset1:164
	s_nop 1
	ds_read2_b64 v[82:85], v146 offset0:168 offset1:172
	s_waitcnt lgkmcnt(4)
	v_mfma_f32_16x16x32_bf16 v[90:93], v[114:117], v[110:113], v[90:93]
	ds_read2_b64 v[118:121], v146 offset0:176 offset1:180
	ds_read2_b64 v[114:117], v146 offset0:184 offset1:188
	v_add_u32_e32 v146, 0xd800, v241
	s_waitcnt lgkmcnt(5)
	v_mfma_f32_16x16x32_bf16 v[176:179], v[122:125], v[78:81], v[90:93]
	ds_read2_b64 v[122:125], v146 offset0:32 offset1:36
	s_nop 1
	ds_read2_b64 v[90:93], v146 offset0:40 offset1:44
	s_waitcnt lgkmcnt(6)
	v_mfma_f32_16x16x32_bf16 v[126:129], v[126:129], v[94:97], v[176:179]
	s_cbranch_vccnz .LBB0_260
	s_and_saveexec_b64 s[62:63], s[2:3]
	s_cbranch_execz .LBB0_273
	v_ashrrev_i32_e32 v169, 31, v168
	v_lshlrev_b64 v[170:171], 10, v[168:169]
	v_lshl_add_u64 v[170:171], v[166:167], 0, v[170:171]
	s_nop 1
	v_cvt_pk_bf16_f32 v146, v126, s0
	flat_store_short v[170:171], v146
	s_or_b64 exec, exec, s[62:63]
	s_and_saveexec_b64 s[62:63], s[16:17]
	s_cbranch_execnz .LBB0_274

.LBB0_307:
	s_or_b64 exec, exec, s[64:65]
	v_add_u32_e32 v90, 0x8800, v241
	s_nop 0
	ds_read2_b64 v[82:85], v90 offset1:4
	v_add_u32_e32 v91, 0x9000, v241
	ds_read2_b64 v[86:89], v91 offset0:32 offset1:36
	v_pk_mul_f32 v[4:5], v[162:163], v[4:5] op_sel_hi:[0,1]
	v_pk_mul_f32 v[2:3], v[162:163], v[2:3] op_sel_hi:[0,1]
	v_pk_mul_f32 v[8:9], v[162:163], v[8:9] op_sel_hi:[0,1]
	v_pk_mul_f32 v[6:7], v[162:163], v[6:7] op_sel_hi:[0,1]
	v_pk_mul_f32 v[12:13], v[162:163], v[12:13] op_sel_hi:[0,1]
	v_pk_mul_f32 v[10:11], v[162:163], v[10:11] op_sel_hi:[0,1]
	s_waitcnt lgkmcnt(0)
	v_mfma_f32_16x16x32_bf16 v[2:5], v[82:85], v[78:81], v[2:5]
	ds_read2_b64 v[82:85], v90 offset0:8 offset1:12
	v_add_u32_e32 v90, 0x9800, v241
	v_pk_mul_f32 v[16:17], v[162:163], v[16:17] op_sel_hi:[0,1]
	v_mfma_f32_16x16x32_bf16 v[6:9], v[86:89], v[78:81], v[6:9]
	ds_read2_b64 v[86:89], v91 offset0:40 offset1:44
	v_pk_mul_f32 v[14:15], v[162:163], v[14:15] op_sel_hi:[0,1]
	v_pk_mul_f32 v[20:21], v[162:163], v[20:21] op_sel_hi:[0,1]
	v_pk_mul_f32 v[18:19], v[162:163], v[18:19] op_sel_hi:[0,1]
	s_waitcnt lgkmcnt(0)
	v_mfma_f32_16x16x32_bf16 v[2:5], v[82:85], v[94:97], v[2:5]
	ds_read2_b64 v[82:85], v90 offset0:64 offset1:68
	ds_read2_b64 v[90:93], v90 offset0:72 offset1:76
	v_pk_mul_f32 v[24:25], v[162:163], v[24:25] op_sel_hi:[0,1]
	v_pk_mul_f32 v[22:23], v[162:163], v[22:23] op_sel_hi:[0,1]
	v_mfma_f32_16x16x32_bf16 v[6:9], v[86:89], v[94:97], v[6:9]
	v_add_u32_e32 v86, 0x8800, v169
	v_add_u32_e32 v98, v240, v207
	v_pk_mul_f32 v[44:45], v[162:163], v[44:45] op_sel_hi:[0,1]
	s_waitcnt lgkmcnt(0)
	v_mfma_f32_16x16x32_bf16 v[10:13], v[82:85], v[78:81], v[10:13]
	ds_read2_b64 v[82:85], v86 offset1:4
	ds_read2_b64 v[86:89], v86 offset0:8 offset1:12
	v_pk_mul_f32 v[42:43], v[162:163], v[42:43] op_sel_hi:[0,1]
	v_pk_mul_f32 v[48:49], v[162:163], v[48:49] op_sel_hi:[0,1]
	v_mfma_f32_16x16x32_bf16 v[10:13], v[90:93], v[94:97], v[10:13]
	v_add_u32_e32 v90, 0xa800, v241
	v_pk_mul_f32 v[46:47], v[162:163], v[46:47] op_sel_hi:[0,1]
	s_waitcnt lgkmcnt(0)
	v_mfma_f32_16x16x32_bf16 v[14:17], v[82:85], v[78:81], v[14:17]
	ds_read2_b64 v[82:85], v90 offset0:128 offset1:132
	ds_read2_b64 v[90:93], v90 offset0:136 offset1:140
	v_mfma_f32_16x16x32_bf16 v[14:17], v[86:89], v[94:97], v[14:17]
	v_add_u32_e32 v86, 0xb000, v241
	s_waitcnt lgkmcnt(0)
	v_mfma_f32_16x16x32_bf16 v[18:21], v[82:85], v[78:81], v[18:21]
	ds_read2_b64 v[82:85], v86 offset0:160 offset1:164
	ds_read2_b64 v[86:89], v86 offset0:168 offset1:172
	v_mfma_f32_16x16x32_bf16 v[18:21], v[90:93], v[94:97], v[18:21]
	v_add_u32_e32 v90, 0xb800, v241
	s_waitcnt lgkmcnt(0)
	v_mfma_f32_16x16x32_bf16 v[22:25], v[82:85], v[78:81], v[22:25]
	ds_read2_b64 v[82:85], v90 offset0:192 offset1:196
	ds_read2_b64 v[90:93], v90 offset0:200 offset1:204
	v_mfma_f32_16x16x32_bf16 v[22:25], v[86:89], v[94:97], v[22:25]
	v_add_u32_e32 v86, 0x8800, v98
	s_waitcnt lgkmcnt(0)
	v_mfma_f32_16x16x32_bf16 v[42:45], v[82:85], v[78:81], v[42:45]
	ds_read2_b64 v[82:85], v86 offset1:4
	ds_read2_b64 v[98:101], v86 offset0:8 offset1:12
	s_waitcnt vmcnt(4)
	v_mov_b32_e32 v162, v239
	v_lshlrev_b32_e32 v26, 16, v26
	v_lshlrev_b32_e32 v27, 16, v27
	v_lshlrev_b32_e32 v28, 16, v28
	v_lshlrev_b32_e32 v29, 16, v29
	v_lshlrev_b32_e32 v30, 16, v30
	v_lshlrev_b32_e32 v31, 16, v31
	v_lshlrev_b32_e32 v32, 16, v32
	v_lshlrev_b32_e32 v33, 16, v33
	v_lshlrev_b32_e32 v34, 16, v34
	v_lshlrev_b32_e32 v35, 16, v35
	v_lshlrev_b32_e32 v36, 16, v36
	v_lshlrev_b32_e32 v37, 16, v37
	v_lshlrev_b32_e32 v38, 16, v38
	v_lshlrev_b32_e32 v39, 16, v39
	v_lshlrev_b32_e32 v40, 16, v40
	v_lshlrev_b32_e32 v41, 16, v41
	v_mov_b64_e32 v[88:89], v[36:37]
	v_mov_b64_e32 v[86:87], v[34:35]
	s_waitcnt lgkmcnt(0)
	v_mfma_f32_16x16x32_bf16 v[46:49], v[82:85], v[78:81], v[46:49]
	v_mov_b64_e32 v[84:85], v[32:33]
	v_mov_b64_e32 v[80:81], v[28:29]
	v_mov_b64_e32 v[82:83], v[30:31]
	v_mfma_f32_16x16x32_bf16 v[42:45], v[90:93], v[94:97], v[42:45]
	v_mov_b64_e32 v[92:93], v[40:41]
	v_mov_b64_e32 v[90:91], v[38:39]
	v_mov_b64_e32 v[78:79], v[26:27]
	v_mfma_f32_16x16x32_bf16 v[46:49], v[98:101], v[94:97], v[46:49]
